# ring combine work placement: the 4 value-tile workgroups of one chain share an XCD (nt=(b>>3)&3, chain=(b&7)+8*(b>>5)) so shared P fragments hit L2; no ring flag changes
# speedup vs baseline: 1.0033x; 1.0006x over previous
.Lw2_done:
	s_or_b64 exec, exec, s[8:9]
	s_lshr_b32 s87, s16, 6
	s_add_u32 s94, s0, 0x1dee0200
	s_addc_u32 s95, s1, 0
	s_add_u32 s98, s0, 0x1dee0400
	s_addc_u32 s99, s1, 0
	s_add_u32 s50, s0, 0x1dee0500
	s_addc_u32 s51, s1, 0
	s_add_u32 s78, s0, 0x1dee0600
	s_addc_u32 s79, s1, 0
	s_add_u32 s80, s0, 0x1dee0700
	s_addc_u32 s81, s1, 0
	s_add_u32 s82, s0, 0x1dee0800
	s_addc_u32 s83, s1, 0
	s_add_u32 s48, s0, 0x1dee0900
	s_addc_u32 s49, s1, 0
	s_add_u32 s52, s0, 0x1dee0a00
	s_addc_u32 s53, s1, 0
	s_add_u32 s54, s0, 0x1dee0b00
	s_addc_u32 s55, s1, 0
	s_add_u32 s58, s0, 0x1dee0c00
	s_addc_u32 s59, s1, 0
	s_waitcnt lgkmcnt(0)
	s_add_u32 s2, s0, 0x1dee0d00
	s_addc_u32 s3, s1, 0
	v_writelane_b32 v253, s2, 1
	s_mul_i32 s57, s57, s56
	s_mov_b32 s97, 0
	v_writelane_b32 v253, s3, 2
	s_add_u32 s2, s0, 0x1dee0e00
	s_addc_u32 s3, s1, 0
	v_writelane_b32 v253, s2, 3
	v_mov_b32_e32 v3, 0
	v_writelane_b32 v255, s90, 0
	v_writelane_b32 v253, s3, 4
	s_add_u32 s2, s0, 0x1dee0f00
	s_addc_u32 s3, s1, 0
	v_writelane_b32 v253, s2, 5
	v_writelane_b32 v255, s91, 1
	v_writelane_b32 v255, s29, 2
	v_writelane_b32 v253, s3, 6
	s_add_u32 s2, s0, 0x1dee1000
	s_addc_u32 s3, s1, 0
	v_writelane_b32 v253, s2, 7
	v_writelane_b32 v255, s85, 3
	v_writelane_b32 v255, s87, 4
	v_writelane_b32 v253, s3, 8
	s_add_u32 s2, s0, 0x1dee1100
	s_addc_u32 s3, s1, 0
	v_writelane_b32 v253, s2, 9
	v_writelane_b32 v255, s94, 5
	v_mov_b32_e32 v240, 1
	v_writelane_b32 v253, s3, 10
	s_add_u32 s2, s0, 0x1dee1200
	s_addc_u32 s3, s1, 0
	v_writelane_b32 v253, s2, 11
	v_writelane_b32 v255, s95, 6
	v_writelane_b32 v255, s98, 7
	v_writelane_b32 v253, s3, 12
	s_add_u32 s2, s0, 0x1dee1300
	s_addc_u32 s3, s1, 0
	v_writelane_b32 v253, s2, 13
	s_cmp_eq_u32 s17, 15
	v_mov_b32_e32 v241, 0x3727c5ac
	v_writelane_b32 v253, s3, 14
	s_cselect_b64 s[2:3], -1, 0
	v_writelane_b32 v253, s2, 15
	s_cmp_eq_u32 s17, 14
	v_mov_b32_e32 v242, 0x260
	v_writelane_b32 v253, s3, 16
	s_cselect_b64 s[2:3], -1, 0
	v_writelane_b32 v253, s2, 17
	s_cmp_eq_u32 s17, 13
	v_mov_b64_e32 v[202:203], 0x83f
	v_writelane_b32 v253, s3, 18
	s_cselect_b64 s[2:3], -1, 0
	v_writelane_b32 v253, s2, 19
	s_cmp_eq_u32 s17, 12
	v_mov_b32_e32 v243, 0x2200
	v_writelane_b32 v253, s3, 20
	s_cselect_b64 s[2:3], -1, 0
	v_writelane_b32 v253, s2, 21
	s_cmp_eq_u32 s17, 11
	v_mov_b32_e32 v244, 0x58
	v_writelane_b32 v253, s3, 22
	s_cselect_b64 s[2:3], -1, 0
	v_writelane_b32 v253, s2, 23
	s_cmp_eq_u32 s17, 10
	v_mov_b32_e32 v245, 0x48
	v_writelane_b32 v253, s3, 24
	s_cselect_b64 s[2:3], -1, 0
	v_writelane_b32 v253, s2, 25
	s_cmp_eq_u32 s17, 9
	s_movk_i32 s31, 0x1000
	v_writelane_b32 v253, s3, 26
	s_cselect_b64 s[2:3], -1, 0
	v_writelane_b32 v253, s2, 27
	s_cmp_eq_u32 s17, 8
	s_movk_i32 s19, 0x2000
	v_writelane_b32 v253, s3, 28
	s_cselect_b64 s[2:3], -1, 0
	v_writelane_b32 v253, s2, 29
	s_cmp_eq_u32 s17, 7
	s_movk_i32 s62, 0x3200
	v_writelane_b32 v253, s3, 30
	s_cselect_b64 s[2:3], -1, 0
	v_writelane_b32 v253, s2, 31
	s_cmp_eq_u32 s17, 6
	s_movk_i32 s63, 0x90
	v_writelane_b32 v253, s3, 32
	s_cselect_b64 s[2:3], -1, 0
	v_writelane_b32 v253, s2, 33
	s_cmp_eq_u32 s17, 5
	s_movk_i32 s64, 0x3000
	v_writelane_b32 v253, s3, 34
	s_cselect_b64 s[2:3], -1, 0
	v_writelane_b32 v253, s2, 35
	s_cmp_eq_u32 s17, 4
	s_mov_b32 s65, 0x800000
	v_writelane_b32 v253, s3, 36
	s_cselect_b64 s[2:3], -1, 0
	v_writelane_b32 v253, s2, 37
	s_cmp_eq_u32 s17, 3
	s_movk_i32 s66, 0x200
	v_writelane_b32 v253, s3, 38
	s_cselect_b64 s[2:3], -1, 0
	v_writelane_b32 v253, s2, 39
	s_cmp_eq_u32 s17, 2
	s_movk_i32 s67, 0x7000
	v_writelane_b32 v253, s3, 40
	s_cselect_b64 s[2:3], -1, 0
	v_writelane_b32 v253, s2, 41
	s_cmp_eq_u32 s17, 1
	s_movk_i32 s68, 0x1ff
	v_writelane_b32 v253, s3, 42
	s_cselect_b64 s[2:3], -1, 0
	v_writelane_b32 v253, s2, 43
	s_cmp_eq_u32 s17, 0
	s_mov_b32 s69, 0xf800000
	v_writelane_b32 v253, s3, 44
	s_cselect_b64 s[2:3], -1, 0
	v_writelane_b32 v253, s2, 45
	s_mov_b32 s92, -1
	s_mov_b64 s[12:13], 0x80
	v_writelane_b32 v253, s3, 46
	s_lshl_b32 s2, s17, 8
	s_add_u32 s2, s4, s2
	s_addc_u32 s3, s5, 0
	s_add_u32 s4, s2, 0x1400
	s_addc_u32 s5, s3, 0
	v_writelane_b32 v253, s4, 47
	s_add_u32 s2, s2, 0x2400
	s_addc_u32 s3, s3, 0
	v_writelane_b32 v253, s5, 48
	v_writelane_b32 v253, s2, 49
	s_mov_b64 s[14:15], 0x1000
	s_mov_b32 s18, 0xbfb8aa3b
	v_writelane_b32 v253, s3, 50
	s_add_u32 s2, s0, 0x1dee3400
	s_addc_u32 s3, s1, 0
	v_writelane_b32 v253, s2, 51
	s_add_u32 s0, s0, 0x1dee3500
	s_addc_u32 s1, s1, 0
	v_writelane_b32 v253, s3, 52
	v_writelane_b32 v253, s0, 53
	s_cmpk_lt_i32 s86, 0x840
	s_mov_b64 s[22:23], 0x1800
	v_writelane_b32 v253, s1, 54
	s_cselect_b64 s[0:1], -1, 0
	v_writelane_b32 v253, s0, 55
	s_ashr_i32 s2, s56, 31
	s_mov_b64 s[24:25], 0x3000
	v_writelane_b32 v253, s1, 56
	s_load_dword s0, s[88:89], 0xb8
	s_mov_b64 s[26:27], 0x4000
	s_mov_b32 s28, 0x3c800000
	s_mov_b32 s30, 0x3f9837f0
	v_writelane_b32 v255, s99, 8
	s_waitcnt lgkmcnt(0)
	s_mul_i32 s57, s57, s0
	s_ashr_i32 s0, s86, 31
	v_writelane_b32 v253, s0, 57
	s_lshr_b32 s0, s0, 29
	s_add_i32 s0, s86, s0
	s_ashr_i32 s1, s0, 3
	s_and_b32 s0, s0, -8
	s_sub_i32 s0, s86, s0
	v_writelane_b32 v253, s2, 58
	s_cmp_gt_u32 s56, 64
	s_mul_i32 s2, s87, 0x1c00
	s_cselect_b64 s[4:5], -1, 0
	s_add_i32 s33, s2, 0
	v_writelane_b32 v253, s4, 59
	s_cmpk_gt_u32 s56, 0x7f
	s_cselect_b64 s[2:3], -1, 0
	v_writelane_b32 v253, s5, 60
	v_writelane_b32 v253, s2, 61
	s_lshl_b32 s76, s56, 3
	s_nop 0
	v_writelane_b32 v253, s3, 62
	s_lshl_b32 s2, s86, 3
	s_cmpk_lt_i32 s86, 0x80
	v_writelane_b32 v253, s2, 63
	s_cselect_b64 s[2:3], -1, 0
	v_writelane_b32 v254, s2, 0
	s_lshr_b32 s96, s86, 5
	s_lshl_b32 s96, s96, 3
	s_and_b32 s2, s86, 7
	s_or_b32 s96, s96, s2
	s_nop 0
	v_writelane_b32 v254, s3, 1
	s_bfe_u32 s2, s86, 0x20003
	s_cmp_gt_u32 s16, 63
	s_cselect_b64 s[4:5], -1, 0
	v_writelane_b32 v254, s4, 2
	s_cmpk_lt_u32 s16, 0x1000
	s_mov_b64 s[16:17], 0x2000
	v_writelane_b32 v254, s5, 3
	s_cselect_b64 s[4:5], -1, 0
	v_writelane_b32 v254, s4, 4
	s_lshl_b32 s3, s2, 10
	s_lshl_b32 s2, s2, 8
	v_writelane_b32 v254, s5, 5
	v_writelane_b32 v254, s3, 6
	v_writelane_b32 v254, s2, 7
	s_lshl_b64 s[2:3], s[96:97], 21
	s_add_i32 s4, s87, -1
	v_writelane_b32 v254, s2, 8
	s_ashr_i32 s5, s4, 31
	s_nop 0
	v_writelane_b32 v254, s3, 9
	s_mov_b32 s2, s4
	v_writelane_b32 v254, s2, 10
	s_nop 1
	v_writelane_b32 v254, s3, 11
	s_lshl_b64 s[2:3], s[4:5], 15
	v_writelane_b32 v254, s2, 12
	s_nop 1
	v_writelane_b32 v254, s3, 13
	s_lshl_b64 s[2:3], s[96:97], 20
	v_writelane_b32 v254, s2, 14
	s_cmpk_lt_i32 s86, 0x100
	s_nop 0
	v_writelane_b32 v254, s3, 15
	s_cselect_b64 s[2:3], -1, 0
	v_writelane_b32 v254, s2, 16
	s_lshl_b32 s8, s56, 5
	s_nop 0
	v_writelane_b32 v254, s3, 17
	s_lshl_b32 s2, s0, 5
	s_cmp_lt_i32 s0, 0
	s_movk_i32 s3, 0x109
	s_cselect_b32 s3, s3, 0x108
	s_mul_i32 s3, s0, s3
	s_mul_i32 s0, s0, 33
	s_cselect_b32 s0, s0, s2
	s_add_i32 s3, s3, s1
	s_mul_hi_i32 s2, s3, 0x3e0f83e1
	s_lshr_b32 s4, s2, 31
	s_ashr_i32 s2, s2, 5
	s_add_i32 s2, s2, s4
	s_mul_i32 s4, s2, 0x84
	s_sub_i32 s3, s3, s4
	s_add_i32 s0, s0, s1
	s_bfe_u32 s4, s3, 0x2001d
	s_ashr_i32 s1, s0, 31
	s_add_i32 s4, s3, s4
	s_lshr_b32 s1, s1, 28
	s_and_b32 s5, s4, 0xfffc
	s_add_i32 s1, s0, s1
	s_sub_i32 s3, s3, s5
	s_and_b32 s5, s1, 0xfff0
	s_sub_i32 s0, s0, s5
	s_bfe_i32 s5, s0, 0x80000
	s_bfe_u32 s5, s5, 0x2000d
	s_add_i32 s5, s0, s5
	s_and_b32 s6, s5, 0xfc
	s_lshl_b32 s2, s2, 2
	s_sext_i32_i16 s3, s3
	s_sub_i32 s0, s0, s6
	s_add_i32 s6, s2, s3
	s_ashr_i32 s1, s1, 4
	s_bfe_i32 s2, s5, 0x80000
	s_lshl_b32 s1, s1, 2
	s_sext_i32_i16 s2, s2
	s_sext_i32_i8 s0, s0
	s_add_i32 s10, s1, s0
	s_ashr_i32 s0, s2, 2
	v_writelane_b32 v254, s0, 18
	s_lshr_b32 s0, s2, 2
	s_bfe_i64 s[0:1], s[0:1], 0x100000
	s_lshl_b64 s[0:1], s[0:1], 20
	s_sext_i32_i16 s4, s4
	v_writelane_b32 v254, s0, 19
	s_ashr_i32 s9, s8, 31
	s_ashr_i32 s11, s10, 31
	v_writelane_b32 v254, s1, 20
	s_ashr_i32 s0, s4, 2
	v_writelane_b32 v254, s0, 21
	s_lshr_b32 s0, s4, 2
	s_bfe_i64 s[0:1], s[0:1], 0x100000
	s_lshl_b64 s[0:1], s[0:1], 19
	v_writelane_b32 v254, s0, 22
	s_ashr_i32 s7, s6, 31
	s_lshl_b32 s77, s56, 4
	v_writelane_b32 v254, s1, 23
	s_lshl_b32 s0, s87, 10
	s_add_i32 s0, s0, 0
	v_writelane_b32 v254, s0, 24
	v_writelane_b32 v254, s8, 25
	s_lshl_b32 s0, s56, 6
	s_movk_i32 s2, 0x4000
	v_writelane_b32 v254, s9, 26
	v_writelane_b32 v254, s0, 27
	s_lshl_b32 s0, s86, 12
	v_writelane_b32 v254, s0, 28
	s_lshl_b32 s0, s56, 12
	v_writelane_b32 v254, s0, 29
	s_lshl_b32 s0, s87, 15
	v_writelane_b32 v254, s0, 30
	s_lshl_b32 s0, s86, 6
	v_writelane_b32 v254, s0, 31
	s_add_i32 s0, 0, 0x23fc0
	v_writelane_b32 v254, s0, 32
	s_add_i32 s0, 0, 0x23fc4
	v_writelane_b32 v254, s0, 33
	s_mov_b32 s0, s10
	v_writelane_b32 v254, s0, 34
	s_movk_i32 s3, 0x6000
	s_nop 0
	v_writelane_b32 v254, s1, 35
	s_lshl_b64 s[0:1], s[10:11], 20
	v_writelane_b32 v254, s0, 36
	s_nop 1
	v_writelane_b32 v254, s1, 37
	s_mov_b32 s0, s6
	v_writelane_b32 v254, s0, 38
	s_nop 1
	v_writelane_b32 v254, s1, 39
	s_lshl_b64 s[0:1], s[6:7], 19
	v_writelane_b32 v254, s0, 40
	s_nop 1
	v_writelane_b32 v254, s1, 41
	s_lshl_b64 s[0:1], s[8:9], 12
	v_writelane_b32 v254, s0, 42
	s_nop 1
	v_writelane_b32 v254, s1, 43
	s_mov_b32 s0, 0xff000000
	v_writelane_b32 v254, s0, 44
	s_nop 1
	v_writelane_b32 v254, s1, 45
	v_writelane_b32 v254, s50, 46
	s_nop 1
	v_writelane_b32 v254, s51, 47
	v_writelane_b32 v254, s78, 48
	s_nop 1
	v_writelane_b32 v254, s79, 49
	v_writelane_b32 v254, s80, 50
	s_nop 1
	v_writelane_b32 v254, s81, 51
	v_writelane_b32 v254, s82, 52
	s_nop 1
	v_writelane_b32 v254, s83, 53
	v_writelane_b32 v254, s48, 54
	s_nop 1
	v_writelane_b32 v254, s49, 55
	v_writelane_b32 v254, s52, 56
	s_nop 1
	v_writelane_b32 v254, s53, 57
	v_writelane_b32 v254, s54, 58
	s_nop 1
	v_writelane_b32 v254, s55, 59
	v_writelane_b32 v254, s58, 60
	s_nop 1
	v_writelane_b32 v254, s59, 61
	v_writelane_b32 v254, s76, 62
	v_writelane_b32 v254, s77, 63
	s_branch .LBB0_30
